# same as previous plus s_nop closing an MFMA-result to VALU-read distance in the C loop (12 wait states)
# baseline (speedup 1.0000x reference)
; #define SBAR() __builtin_amdgcn_sched_barrier(0)
; template <int DQK>
; __device__ __forceinline__ void qkt(f32x16& p0, f32x16& p1, const char* Ks, const bf16x8* qr, int r32, int hi) {
;   constexpr int KP = DQK * 2;
;   p0 = f32x16{}; p1 = f32x16{};
;   if constexpr (DQK == 64 && ATT_KPRELOAD) {
;     bf16x8 ka[4], kq[4];
; #pragma unroll
;     for (int d0 = 0; d0 < 4; ++d0) { const int cb = (d0 * 16 + hi * 8) * 2;
;       ka[d0] = *reinterpret_cast<const bf16x8*>(Ks + KSWZ(KP, r32, cb)); kq[d0] = *reinterpret_cast<const bf16x8*>(Ks + KSWZ(KP, 32 + r32, cb)); }
;     SBAR();
; #pragma unroll
;     for (int d0 = 0; d0 < 4; ++d0) { p0 = __builtin_amdgcn_mfma_f32_32x32x16_bf16(ka[d0], qr[d0], p0, 0, 0, 0); p1 = __builtin_amdgcn_mfma_f32_32x32x16_bf16(kq[d0], qr[d0], p1, 0, 0, 0); }
;     return;
;   }
; #pragma unroll
;   for (int d0 = 0; d0 < DQK / 16; ++d0) { const int cb = (d0 * 16 + hi * 8) * 2;
;     bf16x8 b0 = *reinterpret_cast<const bf16x8*>(Ks + KSWZ(KP, r32, cb));
;     bf16x8 b1 = *reinterpret_cast<const bf16x8*>(Ks + KSWZ(KP, 32 + r32, cb));
;     p0 = __builtin_amdgcn_mfma_f32_32x32x16_bf16(b0, qr[d0], p0, 0, 0, 0);
;     p1 = __builtin_amdgcn_mfma_f32_32x32x16_bf16(b1, qr[d0], p1, 0, 0, 0); }
;     ...
;       constexpr bool LATE = (DQK == 128) ? ((ATT_STAGE_LATE & 2) != 0) : ((ATT_STAGE_LATE & 4) != 0);
;       if constexpr (!LATE) { if (j + 1 < nt) { SWRITE(b ^ 1, 0); } if (j + 2 < nt) { SLOAD(0, (j + 2) * KVBLK); } }
;       SBAR(); qkt<DQK>(pA0, pA1, K_lds + b * SHM_K, qr, r32, hi); SBAR();
;       if constexpr (LATE) { if (j + 1 < nt) { SWRITE(b ^ 1, 0); } if (j + 2 < nt) { SLOAD(0, (j + 2) * KVBLK); } SBAR(); }
;       }
;       const int vb = vb0 + b * SHM_V;
;       if constexpr (DQK != 192) {
;         VF f0, f1; v_issue<0>(f0, vb);
;         partialSM<FIXM>(pA0, pA1, m_reg, mnA, alA, C, thrS, kb0 + j * KVBLK, hi);
;         RESC(alA);
;         finishSM<FIXM>(pA0, pA1, alA, l_reg, pa0, pa1, pa2, pa3, kb0 + j * KVBLK, hi); SBAR();
;         pv_pipe(o, vb, f0, f1, pa0, pa1, pa2, pa3);
;       } else {
;         partialSM<FIXM>(pA0, pA1, m_reg, mnA, alA, C, thrS, kb0 + j * KVBLK, hi);
;         RESC(alA);
;         finishSM<FIXM>(pA0, pA1, alA, l_reg, pa0, pa1, pa2, pa3, kb0 + j * KVBLK, hi); SBAR();
;         pv_d0(o, vb, pa0, pa1, pa2, pa3);
.LBB0_578:
	s_and_b32 s6, s1, 1
	s_waitcnt lgkmcnt(0)
	s_barrier
	s_mul_i32 s7, s6, 0x6000
	s_add_i32 s7, s0, s7
	v_add3_u32 v218, s7, v224, v189
	v_add3_u32 v219, s7, v223, v189
	v_add3_u32 v220, s7, v222, v189
	v_add3_u32 v242, s7, v221, v189
	ds_read_b128 v[64:67], v218
	ds_read_b128 v[68:71], v219
	ds_read_b128 v[72:75], v220
	ds_read_b128 v[76:79], v242
	ds_read_b128 v[172:175], v218 offset:128
	ds_read_b128 v[176:179], v219 offset:128
	ds_read_b128 v[238:241], v220 offset:128
	ds_read_b128 v[214:217], v242 offset:128
	s_waitcnt lgkmcnt(7)
	v_mfma_f32_32x32x16_bf16 v[80:95], v[64:67], v[144:147], 0
	ds_read_b128 v[64:67], v218 offset:256
	s_waitcnt lgkmcnt(7)
	v_mfma_f32_32x32x16_bf16 v[80:95], v[68:71], v[140:143], v[80:95]
	ds_read_b128 v[68:71], v219 offset:256
	s_waitcnt lgkmcnt(7)
	v_mfma_f32_32x32x16_bf16 v[80:95], v[72:75], v[136:139], v[80:95]
	ds_read_b128 v[72:75], v220 offset:256
	s_waitcnt lgkmcnt(7)
	v_mfma_f32_32x32x16_bf16 v[80:95], v[76:79], v[132:135], v[80:95]
	ds_read_b128 v[76:79], v242 offset:256
	s_waitcnt lgkmcnt(7)
	v_mfma_f32_32x32x16_bf16 v[80:95], v[172:175], v[128:131], v[80:95]
	ds_read_b128 v[172:175], v218 offset:12288
	s_waitcnt lgkmcnt(7)
	v_mfma_f32_32x32x16_bf16 v[80:95], v[176:179], v[124:127], v[80:95]
	ds_read_b128 v[176:179], v219 offset:12288
	s_waitcnt lgkmcnt(7)
	v_mfma_f32_32x32x16_bf16 v[80:95], v[238:241], v[120:123], v[80:95]
	ds_read_b128 v[238:241], v220 offset:12288
	s_waitcnt lgkmcnt(7)
	v_mfma_f32_32x32x16_bf16 v[80:95], v[214:217], v[116:119], v[80:95]
	ds_read_b128 v[214:217], v242 offset:12288
	s_waitcnt lgkmcnt(7)
	v_mfma_f32_32x32x16_bf16 v[80:95], v[64:67], v[112:115], v[80:95]
	s_waitcnt lgkmcnt(6)
	v_mfma_f32_32x32x16_bf16 v[80:95], v[68:71], v[108:111], v[80:95]
	s_waitcnt lgkmcnt(5)
	v_mfma_f32_32x32x16_bf16 v[80:95], v[72:75], v[104:107], v[80:95]
	s_waitcnt lgkmcnt(4)
	v_mfma_f32_32x32x16_bf16 v[80:95], v[76:79], v[100:103], v[80:95]
	s_waitcnt lgkmcnt(3)
	v_mfma_f32_32x32x16_bf16 v[64:79], v[172:175], v[144:147], 0
	ds_read_b128 v[172:175], v218 offset:12416
	s_waitcnt lgkmcnt(3)
	v_mfma_f32_32x32x16_bf16 v[64:79], v[176:179], v[140:143], v[64:79]
	ds_read_b128 v[176:179], v219 offset:12416
	s_waitcnt lgkmcnt(3)
	v_mfma_f32_32x32x16_bf16 v[64:79], v[238:241], v[136:139], v[64:79]
	ds_read_b128 v[238:241], v220 offset:12416
	s_waitcnt lgkmcnt(3)
	v_mfma_f32_32x32x16_bf16 v[64:79], v[214:217], v[132:135], v[64:79]
	ds_read_b128 v[214:217], v242 offset:12416
	v_exp_f32_e32 v80, v80
	v_exp_f32_e32 v81, v81
	v_add_f32_e32 v191, 0, v80
	v_exp_f32_e32 v82, v82
	v_add_f32_e32 v191, v81, v191
	v_exp_f32_e32 v83, v83
	s_waitcnt lgkmcnt(3)
	v_mfma_f32_32x32x16_bf16 v[64:79], v[172:175], v[128:131], v[64:79]
	ds_read_b128 v[172:175], v218 offset:12544
	v_lshl_add_u32 v218, s6, 14, v187
	v_add_f32_e32 v191, v82, v191
	v_exp_f32_e32 v84, v84
	v_add_f32_e32 v191, v83, v191
	v_exp_f32_e32 v85, v85
	v_add_f32_e32 v191, v84, v191
	v_exp_f32_e32 v86, v86
	s_waitcnt lgkmcnt(3)
	v_mfma_f32_32x32x16_bf16 v[64:79], v[176:179], v[124:127], v[64:79]
	ds_read_b128 v[176:179], v219 offset:12544
	v_add_f32_e32 v191, v85, v191
	v_exp_f32_e32 v87, v87
	v_add_f32_e32 v191, v86, v191
	v_exp_f32_e32 v88, v88
	v_add_f32_e32 v191, v87, v191
	v_exp_f32_e32 v89, v89
	s_waitcnt lgkmcnt(3)
	v_mfma_f32_32x32x16_bf16 v[64:79], v[238:241], v[120:123], v[64:79]
	ds_read_b128 v[238:241], v220 offset:12544
	v_add_f32_e32 v191, v88, v191
	v_exp_f32_e32 v90, v90
	v_add_f32_e32 v191, v89, v191
	v_exp_f32_e32 v91, v91
	v_add_f32_e32 v191, v90, v191
	v_exp_f32_e32 v92, v92
	s_waitcnt lgkmcnt(3)
	v_mfma_f32_32x32x16_bf16 v[64:79], v[214:217], v[116:119], v[64:79]
	ds_read_b128 v[214:217], v242 offset:12544
	v_add_f32_e32 v191, v91, v191
	v_exp_f32_e32 v93, v93
	v_add_f32_e32 v191, v92, v191
	v_exp_f32_e32 v94, v94
	v_add_f32_e32 v191, v93, v191
	v_exp_f32_e32 v95, v95
	s_waitcnt lgkmcnt(3)
	v_mfma_f32_32x32x16_bf16 v[64:79], v[172:175], v[112:115], v[64:79]
	ds_read_b64_tr_b16 v[172:173], v218 offset:0x200
	ds_read_b64_tr_b16 v[174:175], v218 offset:0xa00
	v_add_f32_e32 v191, v94, v191
	s_nop 0
	v_add_f32_e32 v191, v95, v191
	v_cvt_pk_bf16_f32 v80, v80, v81
	v_cvt_pk_bf16_f32 v81, v82, v83
	v_cvt_pk_bf16_f32 v82, v84, v85
	s_waitcnt lgkmcnt(4)
	v_mfma_f32_32x32x16_bf16 v[64:79], v[176:179], v[108:111], v[64:79]
	ds_read_b64_tr_b16 v[176:177], v218 offset:0x1200
	ds_read_b64_tr_b16 v[178:179], v218 offset:0x1a00
	v_cvt_pk_bf16_f32 v83, v86, v87
	v_cvt_pk_bf16_f32 v84, v88, v89
	v_cvt_pk_bf16_f32 v85, v90, v91
	v_cvt_pk_bf16_f32 v86, v92, v93
	v_cvt_pk_bf16_f32 v87, v94, v95
	ds_read_b64_tr_b16 v[88:89], v218 offset:0x0
	ds_read_b64_tr_b16 v[90:91], v218 offset:0x800
	s_waitcnt lgkmcnt(7)
	v_mfma_f32_32x32x16_bf16 v[64:79], v[238:241], v[104:107], v[64:79]
	ds_read_b64_tr_b16 v[238:239], v218 offset:0x400
	ds_read_b64_tr_b16 v[240:241], v218 offset:0xc00
	ds_read_b64_tr_b16 v[92:93], v218 offset:0x1000
	ds_read_b64_tr_b16 v[94:95], v218 offset:0x1800
	s_waitcnt lgkmcnt(10)
	v_mfma_f32_32x32x16_bf16 v[64:79], v[214:217], v[100:103], v[64:79]
	ds_read_b64_tr_b16 v[214:215], v218 offset:0x1400
	ds_read_b64_tr_b16 v[216:217], v218 offset:0x1c00
	s_nop 1
	s_waitcnt lgkmcnt(6)
	v_mfma_f32_32x32x16_bf16 v[48:63], v[80:83], v[88:91], v[48:63]
	ds_read_b64_tr_b16 v[88:89], v218 offset:0x600
	ds_read_b64_tr_b16 v[90:91], v218 offset:0xe00
	s_nop 3
	v_exp_f32_e32 v64, v64
	v_exp_f32_e32 v65, v65
	v_add_f32_e32 v191, v64, v191
	s_waitcnt lgkmcnt(4)
; #define SBAR() __builtin_amdgcn_sched_barrier(0)
; #define RESC(a) do { if constexpr (!FIXM) if (__any((a) < 1.f)) { if (hi == 0) al_l[r32] = (a); asm volatile("s_waitcnt lgkmcnt(0)" ::: "memory"); \
;     _Pragma("unroll") for (int d = 0; d < 4; ++d) _Pragma("unroll") for (int r = 0; r < 16; ++r) o[d][r] *= al_l[crow(r, hi)]; } } while (0)
; template <int D0> __device__ __forceinline__ void pv_one(f32x16& od, int vb, bf16x8 pa0, bf16x8 pa1, bf16x8 pa2, bf16x8 pa3) {
;   const s16x4 l0 = tr_read<v_rd_off(D0, 0, 0)>(vb), h0 = tr_read<v_rd_off(D0, 0, 1)>(vb), l1 = tr_read<v_rd_off(D0, 1, 0)>(vb), h1 = tr_read<v_rd_off(D0, 1, 1)>(vb);
;   const s16x4 l2 = tr_read<v_rd_off(D0, 2, 0)>(vb), h2 = tr_read<v_rd_off(D0, 2, 1)>(vb), l3 = tr_read<v_rd_off(D0, 3, 0)>(vb), h3 = tr_read<v_rd_off(D0, 3, 1)>(vb);
;   asm volatile("s_waitcnt lgkmcnt(0)" ::: "memory"); SBAR();
;     ...
;   od = __builtin_amdgcn_mfma_f32_32x32x16_bf16(pa0, PK(l0, h0), od, 0, 0, 0);
;   od = __builtin_amdgcn_mfma_f32_32x32x16_bf16(pa1, PK(l1, h1), od, 0, 0, 0);
;   od = __builtin_amdgcn_mfma_f32_32x32x16_bf16(pa2, PK(l2, h2), od, 0, 0, 0);
;   od = __builtin_amdgcn_mfma_f32_32x32x16_bf16(pa3, PK(l3, h3), od, 0, 0, 0);
;     ...
; }
; __device__ __forceinline__ void pv_d0(f32x16* o, int vb, bf16x8 pa0, bf16x8 pa1, bf16x8 pa2, bf16x8 pa3) {
;   pv_one<0>(o[0], vb, pa0, pa1, pa2, pa3); pv_one<1>(o[1], vb, pa0, pa1, pa2, pa3); pv_one<2>(o[2], vb, pa0, pa1, pa2, pa3); pv_one<3>(o[3], vb, pa0, pa1, pa2, pa3);
;     ...
;       } else {
;         partialSM<FIXM>(pA0, pA1, m_reg, mnA, alA, C, thrS, kb0 + j * KVBLK, hi);
;         RESC(alA);
;         finishSM<FIXM>(pA0, pA1, alA, l_reg, pa0, pa1, pa2, pa3, kb0 + j * KVBLK, hi); SBAR();
;         pv_d0(o, vb, pa0, pa1, pa2, pa3);
	v_mfma_f32_32x32x16_bf16 v[48:63], v[84:87], v[92:95], v[48:63]
	ds_read_b64_tr_b16 v[92:93], v218 offset:0x1600
	ds_read_b64_tr_b16 v[94:95], v218 offset:0x1e00
	v_exp_f32_e32 v66, v66
	v_add_f32_e32 v191, v65, v191
	v_exp_f32_e32 v67, v67
	v_add_f32_e32 v191, v66, v191
	v_mfma_f32_32x32x16_bf16 v[32:47], v[80:83], v[172:175], v[32:47]
	ds_read_b64_tr_b16 v[172:173], v218 offset:0x2000
	ds_read_b64_tr_b16 v[174:175], v218 offset:0x2800
	v_exp_f32_e32 v68, v68
	v_add_f32_e32 v191, v67, v191
	v_exp_f32_e32 v69, v69
	v_add_f32_e32 v191, v68, v191
	v_mfma_f32_32x32x16_bf16 v[32:47], v[84:87], v[176:179], v[32:47]
	ds_read_b64_tr_b16 v[176:177], v218 offset:0x3000
	ds_read_b64_tr_b16 v[178:179], v218 offset:0x3800
	v_exp_f32_e32 v70, v70
	v_add_f32_e32 v191, v69, v191
	v_exp_f32_e32 v71, v71
	v_add_f32_e32 v191, v70, v191
	v_mfma_f32_32x32x16_bf16 v[16:31], v[80:83], v[238:241], v[16:31]
	ds_read_b64_tr_b16 v[238:239], v218 offset:0x2200
	ds_read_b64_tr_b16 v[240:241], v218 offset:0x2a00
	v_exp_f32_e32 v72, v72
	v_add_f32_e32 v191, v71, v191
	v_exp_f32_e32 v73, v73
	v_add_f32_e32 v191, v72, v191
	s_waitcnt lgkmcnt(10)
	v_mfma_f32_32x32x16_bf16 v[16:31], v[84:87], v[214:217], v[16:31]
	ds_read_b64_tr_b16 v[214:215], v218 offset:0x3200
	ds_read_b64_tr_b16 v[216:217], v218 offset:0x3a00
	v_exp_f32_e32 v74, v74
	v_add_f32_e32 v191, v73, v191
	v_exp_f32_e32 v75, v75
	v_add_f32_e32 v191, v74, v191
	s_waitcnt lgkmcnt(10)
	v_mfma_f32_32x32x16_bf16 v[0:15], v[80:83], v[88:91], v[0:15]
	ds_read_b64_tr_b16 v[88:89], v218 offset:0x2400
	ds_read_b64_tr_b16 v[90:91], v218 offset:0x2c00
	v_exp_f32_e32 v76, v76
	v_add_f32_e32 v191, v75, v191
	v_exp_f32_e32 v77, v77
	v_add_f32_e32 v191, v76, v191
	s_waitcnt lgkmcnt(10)
	v_mfma_f32_32x32x16_bf16 v[0:15], v[84:87], v[92:95], v[0:15]
	ds_read_b64_tr_b16 v[92:93], v218 offset:0x3400
	ds_read_b64_tr_b16 v[94:95], v218 offset:0x3c00
	v_exp_f32_e32 v78, v78
	v_add_f32_e32 v191, v77, v191
	v_exp_f32_e32 v79, v79
	v_add_f32_e32 v191, v78, v191
	s_nop 0
	v_add_f32_e32 v191, v79, v191
	v_cvt_pk_bf16_f32 v64, v64, v65
	v_cvt_pk_bf16_f32 v65, v66, v67
	v_cvt_pk_bf16_f32 v66, v68, v69
	v_cvt_pk_bf16_f32 v67, v70, v71
	v_cvt_pk_bf16_f32 v68, v72, v73
	v_cvt_pk_bf16_f32 v69, v74, v75
	v_cvt_pk_bf16_f32 v70, v76, v77
	v_cvt_pk_bf16_f32 v71, v78, v79
	v_add_f32_e32 v230, v230, v191
	s_nop 0
	s_waitcnt lgkmcnt(10)
	v_mfma_f32_32x32x16_bf16 v[48:63], v[64:67], v[172:175], v[48:63]
	ds_read_b64_tr_b16 v[172:173], v218 offset:0x2600
	ds_read_b64_tr_b16 v[174:175], v218 offset:0x2e00
	s_xor_b32 s7, s6, 1
	s_lshl_b32 s12, s7, 14
	s_mulk_i32 s7, 0x6000
	s_add_i32 s7, s0, s7
	v_add_u32_e32 v219, s12, v236
	s_waitcnt vmcnt(4)
	ds_write_b128 v219, v[152:155]
	s_waitcnt lgkmcnt(11)
	v_mfma_f32_32x32x16_bf16 v[48:63], v[68:71], v[176:179], v[48:63]
	ds_read_b64_tr_b16 v[176:177], v218 offset:0x3600
	ds_read_b64_tr_b16 v[178:179], v218 offset:0x3e00
	v_add_u32_e32 v219, s12, v237
	s_waitcnt vmcnt(3)
	ds_write_b128 v219, v[148:151]
	s_waitcnt lgkmcnt(12)
	v_mfma_f32_32x32x16_bf16 v[32:47], v[64:67], v[238:241], v[32:47]
	v_add_u32_e32 v219, s7, v225
	s_waitcnt vmcnt(2)
	ds_write_b128 v219, v[164:167]
	s_waitcnt lgkmcnt(11)
	v_mfma_f32_32x32x16_bf16 v[32:47], v[68:71], v[214:217], v[32:47]
	v_add_u32_e32 v219, s7, v226
	s_waitcnt vmcnt(1)
	ds_write_b128 v219, v[160:163]
	s_waitcnt lgkmcnt(10)
	v_mfma_f32_32x32x16_bf16 v[16:31], v[64:67], v[88:91], v[16:31]
	v_add_u32_e32 v219, s7, v227
	s_waitcnt vmcnt(0)
	ds_write_b128 v219, v[156:159]
	s_waitcnt lgkmcnt(9)
	v_mfma_f32_32x32x16_bf16 v[16:31], v[68:71], v[92:95], v[16:31]
	s_mov_b32 s38, s30
	s_mov_b32 s39, s31
	buffer_load_dwordx4 v[152:155], v228, s[28:31], s3 offen
	buffer_load_dwordx4 v[148:151], v229, s[28:31], s3 offen
	buffer_load_dwordx4 v[164:167], v186, s[36:39], s2 offen
	s_waitcnt lgkmcnt(7)
	v_mfma_f32_32x32x16_bf16 v[0:15], v[64:67], v[172:175], v[0:15]
	buffer_load_dwordx4 v[160:163], v188, s[36:39], s2 offen
	buffer_load_dwordx4 v[156:159], v190, s[36:39], s2 offen
	s_add_i32 s1, s1, 1
	s_add_i32 s2, s2, 0x18000
	s_add_i32 s3, s3, 0x20000
	s_cmp_eq_u32 s2, 0x1818000
	s_waitcnt lgkmcnt(4)
	v_mfma_f32_32x32x16_bf16 v[0:15], v[68:71], v[176:179], v[0:15]
	s_cbranch_scc0 .LBB0_578
	v_add_u32_e32 v220, 0x80, v224
	v_add_u32_e32 v219, 0x80, v223
	v_add_u32_e32 v218, 0x80, v222
	v_add_u32_e32 v217, 0x80, v221
	v_add_u32_e32 v216, 0x100, v224
	v_add_u32_e32 v215, 0x100, v223
	v_add_u32_e32 v214, 0x100, v222
	v_add_u32_e32 v191, 0x100, v221
	s_waitcnt lgkmcnt(0)
	s_barrier
; #define SBAR() __builtin_amdgcn_sched_barrier(0)
; #define SLOAD(i, k0) do { const int sv_ = (k0) * (ldv * 2), sk_ = (k0) * (ldk * 2); sr_[i].vs0 = BLD(rsV, vg0 * 2, sv_); sr_[i].vs1 = BLD(rsV, vg1 * 2, sv_); \
;     _Pragma("unroll") for (int q_ = 0; q_ < KPT; ++q_) sr_[i].ks[q_] = BLD(rsK, kg[q_] * 2, sk_); } while (0)
; #define SWRITE(b, i) do { *(bf16x8*)(V_lds + (b) * SHM_V + vst0) = sr_[i].vs0; *(bf16x8*)(V_lds + (b) * SHM_V + vst1) = sr_[i].vs1; \
;     _Pragma("unroll") for (int q_ = 0; q_ < KPT; ++q_) *(bf16x8*)(K_lds + (b) * SHM_K + kst[q_]) = sr_[i].ks[q_]; } while (0)
; #define RESC(a) do { if constexpr (!FIXM) if (__any((a) < 1.f)) { if (hi == 0) al_l[r32] = (a); asm volatile("s_waitcnt lgkmcnt(0)" ::: "memory"); \
;     _Pragma("unroll") for (int d = 0; d < 4; ++d) _Pragma("unroll") for (int r = 0; r < 16; ++r) o[d][r] *= al_l[crow(r, hi)]; } } while (0)
;     ...
;       constexpr bool LATE = (DQK == 128) ? ((ATT_STAGE_LATE & 2) != 0) : ((ATT_STAGE_LATE & 4) != 0);
;       if constexpr (!LATE) { if (j + 1 < nt) { SWRITE(b ^ 1, 0); } if (j + 2 < nt) { SLOAD(0, (j + 2) * KVBLK); } }
;       SBAR(); qkt<DQK>(pA0, pA1, K_lds + b * SHM_K, qr, r32, hi); SBAR();
;       if constexpr (LATE) { if (j + 1 < nt) { SWRITE(b ^ 1, 0); } if (j + 2 < nt) { SLOAD(0, (j + 2) * KVBLK); } SBAR(); }
;       }
;       const int vb = vb0 + b * SHM_V;
;       if constexpr (DQK != 192) {
;         VF f0, f1; v_issue<0>(f0, vb);
;         partialSM<FIXM>(pA0, pA1, m_reg, mnA, alA, C, thrS, kb0 + j * KVBLK, hi);
;         RESC(alA);
;         finishSM<FIXM>(pA0, pA1, alA, l_reg, pa0, pa1, pa2, pa3, kb0 + j * KVBLK, hi); SBAR();
;         pv_pipe(o, vb, f0, f1, pa0, pa1, pa2, pa3);
;       } else {
;         partialSM<FIXM>(pA0, pA1, m_reg, mnA, alA, C, thrS, kb0 + j * KVBLK, hi);
;         RESC(alA);
;         finishSM<FIXM>(pA0, pA1, alA, l_reg, pa0, pa1, pa2, pa3, kb0 + j * KVBLK, hi); SBAR();
;         pv_d0(o, vb, pa0, pa1, pa2, pa3);
	s_add_i32 s1, 0, 0x16000
	v_add3_u32 v68, s1, v224, v189
	ds_read_b128 v[64:67], v68
	v_add3_u32 v176, s1, v223, v189
	ds_read_b128 v[172:175], v176
	s_waitcnt lgkmcnt(1)
	v_mfma_f32_32x32x16_bf16 v[80:95], v[64:67], v[144:147], 0
	ds_read_b128 v[64:67], v68 offset:12288
	s_waitcnt lgkmcnt(1)
	v_mfma_f32_32x32x16_bf16 v[80:95], v[172:175], v[140:143], v[80:95]
	ds_read_b128 v[172:175], v176 offset:12288
	v_add3_u32 v176, s1, v222, v189
	s_waitcnt lgkmcnt(1)
	v_mfma_f32_32x32x16_bf16 v[64:79], v[64:67], v[144:147], 0
	s_waitcnt lgkmcnt(0)
	v_mfma_f32_32x32x16_bf16 v[64:79], v[172:175], v[140:143], v[64:79]
	ds_read_b128 v[172:175], v176
	s_waitcnt lgkmcnt(0)
	v_mfma_f32_32x32x16_bf16 v[80:95], v[172:175], v[136:139], v[80:95]
	ds_read_b128 v[172:175], v176 offset:12288
	v_add3_u32 v176, s1, v221, v189
	s_waitcnt lgkmcnt(0)
	v_mfma_f32_32x32x16_bf16 v[64:79], v[172:175], v[136:139], v[64:79]
	ds_read_b128 v[172:175], v176
	s_waitcnt lgkmcnt(0)
	v_mfma_f32_32x32x16_bf16 v[80:95], v[172:175], v[132:135], v[80:95]
	ds_read_b128 v[172:175], v176 offset:12288
	v_add3_u32 v176, s1, v220, v189
	s_waitcnt lgkmcnt(0)
	v_mfma_f32_32x32x16_bf16 v[64:79], v[172:175], v[132:135], v[64:79]
	ds_read_b128 v[172:175], v176
	s_waitcnt lgkmcnt(0)
	v_mfma_f32_32x32x16_bf16 v[80:95], v[172:175], v[128:131], v[80:95]
	ds_read_b128 v[172:175], v176 offset:12288
	v_add3_u32 v176, s1, v219, v189
	s_waitcnt lgkmcnt(0)
	v_mfma_f32_32x32x16_bf16 v[64:79], v[172:175], v[128:131], v[64:79]
	ds_read_b128 v[172:175], v176
	s_waitcnt lgkmcnt(0)
	v_mfma_f32_32x32x16_bf16 v[80:95], v[172:175], v[124:127], v[80:95]
	ds_read_b128 v[172:175], v176 offset:12288
	v_add3_u32 v176, s1, v218, v189
	s_waitcnt lgkmcnt(0)
	v_mfma_f32_32x32x16_bf16 v[64:79], v[172:175], v[124:127], v[64:79]
	ds_read_b128 v[172:175], v176
	s_waitcnt lgkmcnt(0)
	v_mfma_f32_32x32x16_bf16 v[80:95], v[172:175], v[120:123], v[80:95]
	ds_read_b128 v[172:175], v176 offset:12288
	v_add3_u32 v176, s1, v217, v189
	s_waitcnt lgkmcnt(0)
	v_mfma_f32_32x32x16_bf16 v[64:79], v[172:175], v[120:123], v[64:79]
	ds_read_b128 v[172:175], v176
	s_waitcnt lgkmcnt(0)
	v_mfma_f32_32x32x16_bf16 v[80:95], v[172:175], v[116:119], v[80:95]
	ds_read_b128 v[172:175], v176 offset:12288
	v_add3_u32 v176, s1, v216, v189
	s_waitcnt lgkmcnt(0)
	v_mfma_f32_32x32x16_bf16 v[64:79], v[172:175], v[116:119], v[64:79]
	ds_read_b128 v[172:175], v176
	s_waitcnt lgkmcnt(0)
	v_mfma_f32_32x32x16_bf16 v[80:95], v[172:175], v[112:115], v[80:95]
	ds_read_b128 v[172:175], v176 offset:12288
	v_add3_u32 v176, s1, v215, v189
	s_waitcnt lgkmcnt(0)
	v_mfma_f32_32x32x16_bf16 v[64:79], v[172:175], v[112:115], v[64:79]
	ds_read_b128 v[172:175], v176
	s_waitcnt lgkmcnt(0)
	v_mfma_f32_32x32x16_bf16 v[80:95], v[172:175], v[108:111], v[80:95]
	ds_read_b128 v[172:175], v176 offset:12288
	v_add3_u32 v176, s1, v214, v189
	s_waitcnt lgkmcnt(0)
	v_mfma_f32_32x32x16_bf16 v[64:79], v[172:175], v[108:111], v[64:79]
	ds_read_b128 v[172:175], v176
	s_waitcnt lgkmcnt(0)
	v_mfma_f32_32x32x16_bf16 v[80:95], v[172:175], v[104:107], v[80:95]
	ds_read_b128 v[172:175], v176 offset:12288
	v_add3_u32 v176, s1, v191, v189
	s_waitcnt lgkmcnt(0)
	v_mfma_f32_32x32x16_bf16 v[64:79], v[172:175], v[104:107], v[64:79]
	ds_read_b128 v[172:175], v176
	s_waitcnt lgkmcnt(0)
	v_mfma_f32_32x32x16_bf16 v[80:95], v[172:175], v[100:103], v[80:95]
	ds_read_b128 v[172:175], v176 offset:12288
	s_waitcnt lgkmcnt(0)
	v_mfma_f32_32x32x16_bf16 v[64:79], v[172:175], v[100:103], v[64:79]
	s_waitcnt vmcnt(4)
	ds_write_b128 v231, v[152:155]
	s_waitcnt vmcnt(3)
	ds_write_b128 v232, v[148:151]
	s_waitcnt vmcnt(2)
	ds_write_b128 v233, v[164:167]
	s_waitcnt vmcnt(1)
	ds_write_b128 v234, v[160:163]
	s_waitcnt vmcnt(0)
	ds_write_b128 v235, v[156:159]
	v_exp_f32_e32 v80, v80
	v_exp_f32_e32 v81, v81
	v_exp_f32_e32 v82, v82
	v_exp_f32_e32 v83, v83
	v_exp_f32_e32 v84, v84
	v_exp_f32_e32 v149, v64
	v_add_f32_e32 v64, 0, v80
	v_exp_f32_e32 v85, v85
	v_add_f32_e32 v64, v81, v64
	v_exp_f32_e32 v86, v86
	v_add_f32_e32 v64, v82, v64
	v_exp_f32_e32 v87, v87
	v_add_f32_e32 v64, v83, v64
	v_exp_f32_e32 v88, v88
	v_add_f32_e32 v64, v84, v64
	v_exp_f32_e32 v89, v89
	v_add_f32_e32 v64, v85, v64
	v_exp_f32_e32 v90, v90
	v_add_f32_e32 v64, v86, v64
	v_exp_f32_e32 v91, v91
	v_add_f32_e32 v64, v87, v64
	v_exp_f32_e32 v92, v92
	v_add_f32_e32 v64, v88, v64
	v_exp_f32_e32 v93, v93
	v_add_f32_e32 v64, v89, v64
	v_exp_f32_e32 v94, v94
	v_add_f32_e32 v64, v90, v64
	v_exp_f32_e32 v95, v95
	v_add_f32_e32 v64, v91, v64
	v_add_f32_e32 v64, v92, v64
	v_exp_f32_e32 v150, v65
	v_add_f32_e32 v64, v93, v64
	v_exp_f32_e32 v151, v66
	v_add_f32_e32 v64, v94, v64
	v_exp_f32_e32 v152, v67
	v_add_f32_e32 v64, v95, v64
	v_exp_f32_e32 v153, v68
	v_add_f32_e32 v64, v149, v64
	v_exp_f32_e32 v154, v69
	v_add_f32_e32 v64, v150, v64
	v_exp_f32_e32 v155, v70
	v_add_f32_e32 v64, v151, v64
	v_exp_f32_e32 v156, v71
	v_add_f32_e32 v64, v152, v64
	v_exp_f32_e32 v157, v72
	v_add_f32_e32 v64, v153, v64
	v_exp_f32_e32 v158, v73
	v_add_f32_e32 v64, v154, v64
	v_exp_f32_e32 v159, v74
	v_add_f32_e32 v64, v155, v64
	v_exp_f32_e32 v160, v75
	v_add_f32_e32 v64, v156, v64
	v_exp_f32_e32 v161, v76
	v_add_f32_e32 v64, v157, v64
	v_exp_f32_e32 v162, v77
	v_add_f32_e32 v64, v158, v64
	v_exp_f32_e32 v163, v78
	v_add_f32_e32 v64, v159, v64
	v_exp_f32_e32 v79, v79
	v_add_f32_e32 v64, v160, v64
	v_add_f32_e32 v64, v161, v64
	v_add_f32_e32 v64, v162, v64
	v_add_f32_e32 v64, v163, v64
	v_add_f32_e32 v64, v79, v64
	v_add_u32_e32 v148, 0x4000, v187
	v_add_f32_e32 v164, v230, v64
	v_cvt_pk_bf16_f32 v64, v80, v81
	v_cvt_pk_bf16_f32 v65, v82, v83
	v_cvt_pk_bf16_f32 v66, v84, v85
	v_cvt_pk_bf16_f32 v67, v86, v87
	v_cvt_pk_bf16_f32 v68, v88, v89
	v_cvt_pk_bf16_f32 v69, v90, v91
	v_cvt_pk_bf16_f32 v70, v92, v93
	v_cvt_pk_bf16_f32 v71, v94, v95
	v_cvt_pk_bf16_f32 v72, v149, v150
	v_cvt_pk_bf16_f32 v73, v151, v152
	v_cvt_pk_bf16_f32 v74, v153, v154
	v_cvt_pk_bf16_f32 v75, v155, v156
	v_cvt_pk_bf16_f32 v76, v157, v158
	v_cvt_pk_bf16_f32 v77, v159, v160
	v_cvt_pk_bf16_f32 v78, v161, v162
	v_cvt_pk_bf16_f32 v79, v163, v79
	ds_read_b64_tr_b16 v[80:81], v148 offset:0
	ds_read_b64_tr_b16 v[82:83], v148 offset:0x800
	ds_read_b64_tr_b16 v[84:85], v148 offset:0x1000
	ds_read_b64_tr_b16 v[86:87], v148 offset:0x1800
	ds_read_b64_tr_b16 v[88:89], v148 offset:0x2000
	ds_read_b64_tr_b16 v[90:91], v148 offset:0x2800
	ds_read_b64_tr_b16 v[92:93], v148 offset:0x3000
	ds_read_b64_tr_b16 v[94:95], v148 offset:0x3800
	s_waitcnt lgkmcnt(0)
; #define SBAR() __builtin_amdgcn_sched_barrier(0)
; __device__ __forceinline__ int crow(int r, int hi) { return (r & 3) + 8 * (r >> 2) + 4 * hi; }
; #define SLOAD(i, k0) do { const int sv_ = (k0) * (ldv * 2), sk_ = (k0) * (ldk * 2); sr_[i].vs0 = BLD(rsV, vg0 * 2, sv_); sr_[i].vs1 = BLD(rsV, vg1 * 2, sv_); \
;     _Pragma("unroll") for (int q_ = 0; q_ < KPT; ++q_) sr_[i].ks[q_] = BLD(rsK, kg[q_] * 2, sk_); } while (0)
; #define SWRITE(b, i) do { *(bf16x8*)(V_lds + (b) * SHM_V + vst0) = sr_[i].vs0; *(bf16x8*)(V_lds + (b) * SHM_V + vst1) = sr_[i].vs1; \
;     _Pragma("unroll") for (int q_ = 0; q_ < KPT; ++q_) *(bf16x8*)(K_lds + (b) * SHM_K + kst[q_]) = sr_[i].ks[q_]; } while (0)
; #define RESC(a) do { if constexpr (!FIXM) if (__any((a) < 1.f)) { if (hi == 0) al_l[r32] = (a); asm volatile("s_waitcnt lgkmcnt(0)" ::: "memory"); \
;     _Pragma("unroll") for (int d = 0; d < 4; ++d) _Pragma("unroll") for (int r = 0; r < 16; ++r) o[d][r] *= al_l[crow(r, hi)]; } } while (0)
; template <bool FIXM>
; __device__ __forceinline__ void partialSM(f32x16& p0, f32x16& p1, float& m_reg, float& mn, float& alpha, const float C, const float thrS, const int kb, const int hi) {
;     ...
;     if (kb + KVBLK > LROWS) {
; #pragma unroll
;       for (int r = 0; r < 16; ++r) { if (kb + crow(r, hi) >= LROWS) p0[r] = 0.f; }
;     }
;     ...
;       constexpr bool LATE = (DQK == 128) ? ((ATT_STAGE_LATE & 2) != 0) : ((ATT_STAGE_LATE & 4) != 0);
;       if constexpr (!LATE) { if (j + 1 < nt) { SWRITE(b ^ 1, 0); } if (j + 2 < nt) { SLOAD(0, (j + 2) * KVBLK); } }
;       SBAR(); qkt<DQK>(pA0, pA1, K_lds + b * SHM_K, qr, r32, hi); SBAR();
;       if constexpr (LATE) { if (j + 1 < nt) { SWRITE(b ^ 1, 0); } if (j + 2 < nt) { SLOAD(0, (j + 2) * KVBLK); } SBAR(); }
;       }
;       const int vb = vb0 + b * SHM_V;
;       if constexpr (DQK != 192) {
;         VF f0, f1; v_issue<0>(f0, vb);
;         partialSM<FIXM>(pA0, pA1, m_reg, mnA, alA, C, thrS, kb0 + j * KVBLK, hi);
;         RESC(alA);
;         finishSM<FIXM>(pA0, pA1, alA, l_reg, pa0, pa1, pa2, pa3, kb0 + j * KVBLK, hi); SBAR();
;         pv_pipe(o, vb, f0, f1, pa0, pa1, pa2, pa3);
;       } else {
;         partialSM<FIXM>(pA0, pA1, m_reg, mnA, alA, C, thrS, kb0 + j * KVBLK, hi);
;         RESC(alA);
;         finishSM<FIXM>(pA0, pA1, alA, l_reg, pa0, pa1, pa2, pa3, kb0 + j * KVBLK, hi); SBAR();
;         pv_d0(o, vb, pa0, pa1, pa2, pa3);
	s_nop 0
	v_mfma_f32_32x32x16_bf16 v[48:63], v[64:67], v[80:83], v[48:63]
	ds_read_b64_tr_b16 v[80:81], v148 offset:0x200
	ds_read_b64_tr_b16 v[82:83], v148 offset:0xa00
	v_mfma_f32_32x32x16_bf16 v[48:63], v[68:71], v[84:87], v[48:63]
	ds_read_b64_tr_b16 v[84:85], v148 offset:0x1200
	ds_read_b64_tr_b16 v[86:87], v148 offset:0x1a00
	v_mfma_f32_32x32x16_bf16 v[48:63], v[72:75], v[88:91], v[48:63]
	ds_read_b64_tr_b16 v[88:89], v148 offset:0x2200
	ds_read_b64_tr_b16 v[90:91], v148 offset:0x2a00
	v_mfma_f32_32x32x16_bf16 v[48:63], v[76:79], v[92:95], v[48:63]
	ds_read_b64_tr_b16 v[92:93], v148 offset:0x3200
	ds_read_b64_tr_b16 v[94:95], v148 offset:0x3a00
	s_waitcnt lgkmcnt(0)
	v_mfma_f32_32x32x16_bf16 v[32:47], v[64:67], v[80:83], v[32:47]
	ds_read_b64_tr_b16 v[80:81], v148 offset:0x400
	ds_read_b64_tr_b16 v[82:83], v148 offset:0xc00
	v_mfma_f32_32x32x16_bf16 v[32:47], v[68:71], v[84:87], v[32:47]
	ds_read_b64_tr_b16 v[84:85], v148 offset:0x1400
	ds_read_b64_tr_b16 v[86:87], v148 offset:0x1c00
	v_mfma_f32_32x32x16_bf16 v[32:47], v[72:75], v[88:91], v[32:47]
	ds_read_b64_tr_b16 v[88:89], v148 offset:0x2400
	ds_read_b64_tr_b16 v[90:91], v148 offset:0x2c00
	v_mfma_f32_32x32x16_bf16 v[32:47], v[76:79], v[92:95], v[32:47]
	ds_read_b64_tr_b16 v[92:93], v148 offset:0x3400
	ds_read_b64_tr_b16 v[94:95], v148 offset:0x3c00
	s_waitcnt lgkmcnt(0)
	v_mfma_f32_32x32x16_bf16 v[16:31], v[64:67], v[80:83], v[16:31]
	ds_read_b64_tr_b16 v[80:81], v148 offset:0x600
	ds_read_b64_tr_b16 v[82:83], v148 offset:0xe00
	v_mfma_f32_32x32x16_bf16 v[16:31], v[68:71], v[84:87], v[16:31]
	ds_read_b64_tr_b16 v[84:85], v148 offset:0x1600
	ds_read_b64_tr_b16 v[86:87], v148 offset:0x1e00
	v_mfma_f32_32x32x16_bf16 v[16:31], v[72:75], v[88:91], v[16:31]
	ds_read_b64_tr_b16 v[88:89], v148 offset:0x2600
	ds_read_b64_tr_b16 v[90:91], v148 offset:0x2e00
	v_mfma_f32_32x32x16_bf16 v[16:31], v[76:79], v[92:95], v[16:31]
	ds_read_b64_tr_b16 v[92:93], v148 offset:0x3600
	ds_read_b64_tr_b16 v[94:95], v148 offset:0x3e00
	s_waitcnt lgkmcnt(0)
	v_mfma_f32_32x32x16_bf16 v[0:15], v[64:67], v[80:83], v[0:15]
	v_and_b32_e32 v148, 0x3fffffc0, v213
	s_waitcnt lgkmcnt(0)
	s_barrier
	v_mfma_f32_32x32x16_bf16 v[0:15], v[68:71], v[84:87], v[0:15]
	v_mfma_f32_32x32x16_bf16 v[0:15], v[72:75], v[88:91], v[0:15]
	v_mfma_f32_32x32x16_bf16 v[0:15], v[76:79], v[92:95], v[0:15]
	v_add3_u32 v64, s0, v224, v189
	ds_read_b128 v[64:67], v64
	v_add3_u32 v80, s0, v223, v189
	ds_read_b128 v[80:83], v80
	s_waitcnt lgkmcnt(1)
	v_mfma_f32_32x32x16_bf16 v[64:79], v[64:67], v[144:147], 0
	s_waitcnt lgkmcnt(0)
	v_mfma_f32_32x32x16_bf16 v[64:79], v[80:83], v[140:143], v[64:79]
	v_add3_u32 v80, s0, v222, v189
	ds_read_b128 v[80:83], v80
	s_waitcnt lgkmcnt(0)
	v_mfma_f32_32x32x16_bf16 v[64:79], v[80:83], v[136:139], v[64:79]
	v_add3_u32 v80, s0, v221, v189
	ds_read_b128 v[80:83], v80
	s_waitcnt lgkmcnt(0)
	v_mfma_f32_32x32x16_bf16 v[64:79], v[80:83], v[132:135], v[64:79]
	v_add3_u32 v80, s0, v220, v189
	ds_read_b128 v[80:83], v80
	s_waitcnt lgkmcnt(0)
	v_mfma_f32_32x32x16_bf16 v[64:79], v[80:83], v[128:131], v[64:79]
	v_add3_u32 v80, s0, v219, v189
	ds_read_b128 v[80:83], v80
	s_waitcnt lgkmcnt(0)
	v_mfma_f32_32x32x16_bf16 v[64:79], v[80:83], v[124:127], v[64:79]
	v_add3_u32 v80, s0, v218, v189
	ds_read_b128 v[80:83], v80
	s_waitcnt lgkmcnt(0)
	v_mfma_f32_32x32x16_bf16 v[64:79], v[80:83], v[120:123], v[64:79]
	v_add3_u32 v80, s0, v217, v189
	ds_read_b128 v[80:83], v80
	s_waitcnt lgkmcnt(0)
	v_mfma_f32_32x32x16_bf16 v[64:79], v[80:83], v[116:119], v[64:79]
	v_add3_u32 v80, s0, v216, v189
	ds_read_b128 v[80:83], v80
	s_waitcnt lgkmcnt(0)
	v_mfma_f32_32x32x16_bf16 v[64:79], v[80:83], v[112:115], v[64:79]
	v_add3_u32 v80, s0, v215, v189
	ds_read_b128 v[80:83], v80
	s_waitcnt lgkmcnt(0)
	v_mfma_f32_32x32x16_bf16 v[64:79], v[80:83], v[108:111], v[64:79]
	v_add3_u32 v80, s0, v214, v189
	ds_read_b128 v[80:83], v80
	s_waitcnt lgkmcnt(0)
	v_mfma_f32_32x32x16_bf16 v[64:79], v[80:83], v[104:107], v[64:79]
	v_add3_u32 v80, s0, v191, v189
	ds_read_b128 v[80:83], v80
	s_waitcnt lgkmcnt(0)
	v_mfma_f32_32x32x16_bf16 v[64:79], v[80:83], v[100:103], v[64:79]
	s_nop 11
	v_exp_f32_e32 v72, v64
	v_exp_f32_e32 v65, v65
	v_exp_f32_e32 v73, v66
	v_exp_f32_e32 v67, v67
	v_exp_f32_e32 v68, v68
	v_add_f32_e32 v64, 0, v72
	v_exp_f32_e32 v69, v69
	v_add_f32_e32 v64, v65, v64
	v_exp_f32_e32 v70, v70
	v_add_f32_e32 v64, v73, v64
	v_exp_f32_e32 v71, v71
	v_add_f32_e32 v64, v67, v64
	v_add_f32_e32 v64, v68, v64
	v_add_f32_e32 v64, v69, v64
	v_add_f32_e32 v64, v70, v64
	v_add_f32_e32 v64, v71, v64
	v_add_f32_e32 v64, 0, v64
	v_add_f32_e32 v64, v164, v64
	v_cvt_pk_bf16_f32 v66, v72, v65
	v_cvt_pk_bf16_f32 v67, v73, v67
	v_cvt_pk_bf16_f32 v68, v68, v69
	v_cvt_pk_bf16_f32 v69, v70, v71
	v_cvt_pk_bf16_f32 v70, v169, v169
	v_cvt_pk_bf16_f32 v71, v169, v169
	v_cvt_pk_bf16_f32 v72, v169, v169
	v_cvt_pk_bf16_f32 v73, v169, v169
	v_cvt_pk_bf16_f32 v74, v169, v169
	v_cvt_pk_bf16_f32 v75, v169, v169
	v_cvt_pk_bf16_f32 v76, v169, v169
	v_cvt_pk_bf16_f32 v77, v169, v169
	v_cvt_pk_bf16_f32 v78, v169, v169
	v_cvt_pk_bf16_f32 v79, v169, v169
	v_cvt_pk_bf16_f32 v80, v169, v169
	v_cvt_pk_bf16_f32 v81, v169, v169
	ds_read_b64_tr_b16 v[82:83], v187 offset:0
	ds_read_b64_tr_b16 v[84:85], v187 offset:0x800
	ds_read_b64_tr_b16 v[86:87], v187 offset:0x1000
	ds_read_b64_tr_b16 v[88:89], v187 offset:0x1800
	ds_read_b64_tr_b16 v[90:91], v187 offset:0x2000
	ds_read_b64_tr_b16 v[92:93], v187 offset:0x2800
	ds_read_b64_tr_b16 v[100:101], v187 offset:0x3000
	ds_read_b64_tr_b16 v[102:103], v187 offset:0x3800
	s_waitcnt lgkmcnt(0)
; __device__ __forceinline__ int crow(int r, int hi) { return (r & 3) + 8 * (r >> 2) + 4 * hi; }
; __device__ __forceinline__ float bf2f(unsigned short b) { return __uint_as_float((unsigned)b << 16); }
; __device__ __forceinline__ unsigned f2bf(float f) { unsigned u = __float_as_uint(f); return (u + 0x7fffu + ((u >> 16) & 1u)) >> 16; }
; __device__ __forceinline__ float bf2f(unsigned short b) { return __uint_as_float((unsigned)b << 16); }
; __device__ __forceinline__ unsigned f2bf(float f) { unsigned u = __float_as_uint(f); return (u + 0x7fffu + ((u >> 16) & 1u)) >> 16; }
;     ...
;   { auto rr = __builtin_amdgcn_permlane32_swap(__float_as_uint(l_reg), __float_as_uint(l_reg), false, false);
;     l_reg = __uint_as_float(rr[0]) + __uint_as_float(rr[1]); }
;   if constexpr (SPLIT) if (part != nullptr) {
;     if (wid == 0) {
; #pragma unroll
;       for (int r = 0; r < 16; ++r) { const int orow = crow(r, hi);
;         if (orow < 16) {
; #pragma unroll
;           for (int d0 = 0; d0 < 4; ++d0) part[orow * 132 + d0 * 32 + r32] = o[d0][r]; } }
;       if (hi == 0 && r32 < 16) { part[r32 * 132 + 128] = m_reg; part[r32 * 132 + 129] = l_reg; }
;     }
;     __syncthreads();
;     return;
;   }
;   if (hi == 0) li_l[r32] = l_reg; asm volatile("s_waitcnt lgkmcnt(0)" ::: "memory");
; #pragma unroll
;   for (int r = 0; r < 16; ++r) { const int orow = wid * QBLK + crow(r, hi); const float rli = __builtin_amdgcn_rcpf(li_l[crow(r, hi)]);
;     if (orow < nvalid) {
;       if constexpr (MODE == 0) {
; #pragma unroll
;         for (int d0 = 0; d0 < 4; ++d0) Of[(long)orow * ldo + d0 * 32 + r32] = o[d0][r] * rli;
;       } else {
; #pragma unroll
;         for (int d0 = 0; d0 < 4; ++d0) { const float g = bf2f(Gb[(long)orow * ldg + d0 * 32 + r32]); const float sg = g / (1.f + __expf(-g));
;           Yb[(long)orow * ldy + d0 * 32 + r32] = (bf16)f2bf(o[d0][r] * rli * sg); }
	s_nop 0
	v_mfma_f32_32x32x16_bf16 v[48:63], v[66:69], v[82:85], v[48:63]
	ds_read_b64_tr_b16 v[82:83], v187 offset:0x200
	ds_read_b64_tr_b16 v[84:85], v187 offset:0xa00
	v_mfma_f32_32x32x16_bf16 v[48:63], v[70:73], v[86:89], v[48:63]
	ds_read_b64_tr_b16 v[86:87], v187 offset:0x1200
	ds_read_b64_tr_b16 v[88:89], v187 offset:0x1a00
	v_mfma_f32_32x32x16_bf16 v[48:63], v[74:77], v[90:93], v[48:63]
	ds_read_b64_tr_b16 v[90:91], v187 offset:0x2200
	ds_read_b64_tr_b16 v[92:93], v187 offset:0x2a00
	v_mfma_f32_32x32x16_bf16 v[48:63], v[78:81], v[100:103], v[48:63]
	ds_read_b64_tr_b16 v[100:101], v187 offset:0x3200
	ds_read_b64_tr_b16 v[102:103], v187 offset:0x3a00
	s_waitcnt lgkmcnt(0)
	v_mfma_f32_32x32x16_bf16 v[32:47], v[66:69], v[82:85], v[32:47]
	ds_read_b64_tr_b16 v[82:83], v187 offset:0x400
	ds_read_b64_tr_b16 v[84:85], v187 offset:0xc00
	v_mfma_f32_32x32x16_bf16 v[32:47], v[70:73], v[86:89], v[32:47]
	ds_read_b64_tr_b16 v[86:87], v187 offset:0x1400
	ds_read_b64_tr_b16 v[88:89], v187 offset:0x1c00
	v_mfma_f32_32x32x16_bf16 v[32:47], v[74:77], v[90:93], v[32:47]
	ds_read_b64_tr_b16 v[90:91], v187 offset:0x2400
	ds_read_b64_tr_b16 v[92:93], v187 offset:0x2c00
	v_mfma_f32_32x32x16_bf16 v[32:47], v[78:81], v[100:103], v[32:47]
	ds_read_b64_tr_b16 v[100:101], v187 offset:0x3400
	ds_read_b64_tr_b16 v[102:103], v187 offset:0x3c00
	s_waitcnt lgkmcnt(0)
	v_mfma_f32_32x32x16_bf16 v[16:31], v[66:69], v[82:85], v[16:31]
	ds_read_b64_tr_b16 v[82:83], v187 offset:0x600
	ds_read_b64_tr_b16 v[84:85], v187 offset:0xe00
	v_mfma_f32_32x32x16_bf16 v[16:31], v[70:73], v[86:89], v[16:31]
	ds_read_b64_tr_b16 v[86:87], v187 offset:0x1600
	ds_read_b64_tr_b16 v[88:89], v187 offset:0x1e00
	v_mfma_f32_32x32x16_bf16 v[16:31], v[74:77], v[90:93], v[16:31]
	ds_read_b64_tr_b16 v[90:91], v187 offset:0x2600
	ds_read_b64_tr_b16 v[92:93], v187 offset:0x2e00
	v_mfma_f32_32x32x16_bf16 v[16:31], v[78:81], v[100:103], v[16:31]
	ds_read_b64_tr_b16 v[100:101], v187 offset:0x3600
	ds_read_b64_tr_b16 v[102:103], v187 offset:0x3e00
	s_waitcnt lgkmcnt(0)
	v_mfma_f32_32x32x16_bf16 v[0:15], v[66:69], v[82:85], v[0:15]
	s_add_i32 s0, 0, 0x20000
	v_mov_b32_e32 v65, v64
	v_lshl_add_u32 v69, v148, 2, s0
	s_nop 0
	v_permlane32_swap_b32_e32 v64, v65
	v_cmp_gt_u32_e32 vcc, 32, v195
	v_mfma_f32_32x32x16_bf16 v[0:15], v[70:73], v[86:89], v[0:15]
	v_mfma_f32_32x32x16_bf16 v[0:15], v[74:77], v[90:93], v[0:15]
	v_mfma_f32_32x32x16_bf16 v[0:15], v[78:81], v[100:103], v[0:15]
	s_and_saveexec_b64 s[0:1], vcc
	v_lshl_add_u32 v66, v193, 2, v69
	v_add_f32_e32 v64, v64, v65
	ds_write_b32 v66, v64
	s_or_b64 exec, exec, s[0:1]
	s_lshl_b64 s[0:1], s[4:5], 12
	s_lshl_b32 s2, s97, 7
	s_mul_i32 s6, s4, 0x2e00
	s_mul_hi_u32 s3, s4, 0x2e00
	s_add_u32 s6, s10, s6
	s_addc_u32 s7, s11, s3
	v_readlane_b32 s18, v252, 49
	v_readlane_b32 s19, v252, 50
	s_add_u32 s12, s18, s0
	s_addc_u32 s18, s19, s1
	s_ashr_i32 s3, s2, 31
	s_lshl_b64 s[0:1], s[2:3], 1
	s_add_u32 s2, s12, s0
	s_addc_u32 s3, s18, s1
	s_add_u32 s0, s6, s0
	s_addc_u32 s1, s7, s1
	s_waitcnt lgkmcnt(0)
	v_lshlrev_b32_e32 v72, 2, v194
	v_lshlrev_b32_e32 v64, 1, v193
	v_mov_b32_e32 v65, v169
	v_lshl_add_u64 v[66:67], s[0:1], 0, v[64:65]
	s_mov_b64 s[0:1], 0x2180
	v_or_b32_e32 v68, v72, v192
	v_lshl_add_u64 v[66:67], v[66:67], 0, s[0:1]
	v_lshl_add_u64 v[64:65], s[2:3], 0, v[64:65]
	v_cmp_gt_i32_e32 vcc, s96, v68
	v_lshl_add_u32 v73, v72, 2, v69
	s_and_saveexec_b64 s[0:1], vcc
	s_cbranch_execz .LBB0_583
	v_mad_i64_i32 v[70:71], s[2:3], v68, s20, v[66:67]
	global_load_ushort v75, v[70:71], off
	global_load_ushort v100, v[70:71], off offset:64
	global_load_ushort v101, v[70:71], off offset:128
	global_load_ushort v102, v[70:71], off offset:192
	ds_read_b32 v69, v73
	s_waitcnt lgkmcnt(0)
	v_rcp_f32_e32 v74, v69
	v_ashrrev_i32_e32 v69, 31, v68
	v_lshlrev_b64 v[68:69], 12, v[68:69]
	v_lshl_add_u64 v[68:69], v[64:65], 0, v[68:69]
	v_mul_f32_e32 v48, v48, v74
	v_mul_f32_e32 v32, v32, v74
	v_mul_f32_e32 v16, v16, v74
	v_mul_f32_e32 v0, v0, v74
	s_waitcnt vmcnt(0)
	v_lshlrev_b32_e32 v75, 16, v75
	v_mul_f32_e32 v76, 0xbfb8aa3b, v75
	v_exp_f32_e32 v76, v76
	s_nop 0
	v_add_f32_e32 v76, 1.0, v76
	v_div_scale_f32 v77, s[2:3], v76, v76, v75
	v_rcp_f32_e32 v78, v77
	s_nop 0
	v_fma_f32 v79, -v77, v78, 1.0
	v_fmac_f32_e32 v78, v79, v78
	v_div_scale_f32 v79, vcc, v75, v76, v75
	v_mul_f32_e32 v80, v79, v78
	v_fma_f32 v81, -v77, v80, v79
	v_fmac_f32_e32 v80, v81, v78
	v_fma_f32 v77, -v77, v80, v79
	v_div_fmas_f32 v77, v77, v78, v80
	v_div_fixup_f32 v75, v77, v76, v75
	v_mul_f32_e32 v48, v48, v75
	v_bfe_u32 v75, v48, 16, 1
	v_add3_u32 v48, v48, v75, s15
	global_store_short_d16_hi v[68:69], v48, off offset:2048


; __device__ __forceinline__ float bf2f(unsigned short b) { return __uint_as_float((unsigned)b << 16); }
; __device__ __forceinline__ unsigned f2bf(float f) { unsigned u = __float_as_uint(f); return (u + 0x7fffu + ((u >> 16) & 1u)) >> 16; }
; __device__ __forceinline__ float bf2f(unsigned short b) { return __uint_as_float((unsigned)b << 16); }
; __device__ __forceinline__ unsigned f2bf(float f) { unsigned u = __float_as_uint(f); return (u + 0x7fffu + ((u >> 16) & 1u)) >> 16; }
;     ...
;         for (int d0 = 0; d0 < 4; ++d0) { const float g = bf2f(Gb[(long)orow * ldg + d0 * 32 + r32]); const float sg = g / (1.f + __expf(-g));
;           Yb[(long)orow * ldy + d0 * 32 + r32] = (bf16)f2bf(o[d0][r] * rli * sg); }
	v_lshlrev_b32_e32 v48, 16, v100
	v_mul_f32_e32 v75, 0xbfb8aa3b, v48
	v_exp_f32_e32 v75, v75
	s_nop 0
	v_add_f32_e32 v75, 1.0, v75
	v_div_scale_f32 v76, s[2:3], v75, v75, v48
	v_rcp_f32_e32 v77, v76
	s_nop 0
	v_fma_f32 v78, -v76, v77, 1.0
	v_fmac_f32_e32 v77, v78, v77
	v_div_scale_f32 v78, vcc, v48, v75, v48
	v_mul_f32_e32 v79, v78, v77
	v_fma_f32 v80, -v76, v79, v78
	v_fmac_f32_e32 v79, v80, v77
	v_fma_f32 v76, -v76, v79, v78
	v_div_fmas_f32 v76, v76, v77, v79
	v_div_fixup_f32 v48, v76, v75, v48
	v_mul_f32_e32 v32, v32, v48
	v_bfe_u32 v48, v32, 16, 1
	v_add3_u32 v32, v32, v48, s15
	global_store_short_d16_hi v[68:69], v32, off offset:2112


; __device__ __forceinline__ float bf2f(unsigned short b) { return __uint_as_float((unsigned)b << 16); }
; __device__ __forceinline__ unsigned f2bf(float f) { unsigned u = __float_as_uint(f); return (u + 0x7fffu + ((u >> 16) & 1u)) >> 16; }
; __device__ __forceinline__ float bf2f(unsigned short b) { return __uint_as_float((unsigned)b << 16); }
; __device__ __forceinline__ unsigned f2bf(float f) { unsigned u = __float_as_uint(f); return (u + 0x7fffu + ((u >> 16) & 1u)) >> 16; }
;     ...
;         for (int d0 = 0; d0 < 4; ++d0) { const float g = bf2f(Gb[(long)orow * ldg + d0 * 32 + r32]); const float sg = g / (1.f + __expf(-g));
;           Yb[(long)orow * ldy + d0 * 32 + r32] = (bf16)f2bf(o[d0][r] * rli * sg); }
	v_lshlrev_b32_e32 v32, 16, v101
	v_mul_f32_e32 v48, 0xbfb8aa3b, v32
	v_exp_f32_e32 v48, v48
	s_nop 0
	v_add_f32_e32 v48, 1.0, v48
	v_div_scale_f32 v75, s[2:3], v48, v48, v32
	v_rcp_f32_e32 v76, v75
	s_nop 0
	v_fma_f32 v77, -v75, v76, 1.0
	v_fmac_f32_e32 v76, v77, v76
	v_div_scale_f32 v77, vcc, v32, v48, v32
	v_mul_f32_e32 v78, v77, v76
	v_fma_f32 v79, -v75, v78, v77
	v_fmac_f32_e32 v78, v79, v76
	v_fma_f32 v75, -v75, v78, v77
	v_div_fmas_f32 v75, v75, v76, v78
	v_div_fixup_f32 v32, v75, v48, v32
	v_mul_f32_e32 v16, v16, v32
	v_bfe_u32 v32, v16, 16, 1
	v_add3_u32 v16, v16, v32, s15
	global_store_short_d16_hi v[68:69], v16, off offset:2176


; __device__ __forceinline__ float bf2f(unsigned short b) { return __uint_as_float((unsigned)b << 16); }
; __device__ __forceinline__ unsigned f2bf(float f) { unsigned u = __float_as_uint(f); return (u + 0x7fffu + ((u >> 16) & 1u)) >> 16; }
; __device__ __forceinline__ float bf2f(unsigned short b) { return __uint_as_float((unsigned)b << 16); }
; __device__ __forceinline__ unsigned f2bf(float f) { unsigned u = __float_as_uint(f); return (u + 0x7fffu + ((u >> 16) & 1u)) >> 16; }
;     ...
;         for (int d0 = 0; d0 < 4; ++d0) { const float g = bf2f(Gb[(long)orow * ldg + d0 * 32 + r32]); const float sg = g / (1.f + __expf(-g));
;           Yb[(long)orow * ldy + d0 * 32 + r32] = (bf16)f2bf(o[d0][r] * rli * sg); }
	v_lshlrev_b32_e32 v16, 16, v102
	v_mul_f32_e32 v32, 0xbfb8aa3b, v16
	v_exp_f32_e32 v32, v32
	s_nop 0
	v_add_f32_e32 v32, 1.0, v32
	v_div_scale_f32 v48, s[2:3], v32, v32, v16
	v_rcp_f32_e32 v70, v48
	s_nop 0
	v_fma_f32 v71, -v48, v70, 1.0
	v_fmac_f32_e32 v70, v71, v70
	v_div_scale_f32 v71, vcc, v16, v32, v16
	v_mul_f32_e32 v75, v71, v70
	v_fma_f32 v76, -v48, v75, v71
	v_fmac_f32_e32 v75, v76, v70
	v_fma_f32 v48, -v48, v75, v71
	v_div_fmas_f32 v48, v48, v70, v75
	v_div_fixup_f32 v16, v48, v32, v16
	v_mul_f32_e32 v0, v0, v16
	v_bfe_u32 v16, v0, 16, 1
	v_add3_u32 v0, v0, v16, s15
	global_store_short_d16_hi v[68:69], v0, off offset:2240
